# all small edits combined: indexer interleave, gather permlane reduction + mask-free body + cvt_pk epilogue, barrier polls without sleep
# speedup vs baseline: 1.0097x; 1.0070x over previous
.Lg_join:
	v_cvt_pk_bf16_f32 v8, v11, v13
	v_cvt_pk_bf16_f32 v9, v30, v57
	v_add_f32_e32 v30, v42, v57
	v_add_f32_e32 v30, v30, v31
	ds_read_b64_tr_b16 v[10:11], v89
	ds_read_b64_tr_b16 v[12:13], v90
	ds_read_b64_tr_b16 v[38:39], v91
	ds_read_b64_tr_b16 v[40:41], v92
	ds_read_b64_tr_b16 v[34:35], v93
	ds_read_b64_tr_b16 v[36:37], v94
	ds_read_b64_tr_b16 v[170:171], v95
	ds_read_b64_tr_b16 v[172:173], v96
	s_waitcnt lgkmcnt(0)
	s_nop 0
	v_mfma_f32_16x16x32_bf16 v[10:13], v[6:9], v[10:13], v[182:185]
	v_mov_b32_e32 v31, v30
	s_nop 1
	v_permlane16_swap_b32_e32 v30, v31
	v_mfma_f32_16x16x32_bf16 v[38:41], v[6:9], v[38:41], v[174:177]
	v_add_f32_e32 v30, v30, v31
	v_mfma_f32_16x16x32_bf16 v[34:37], v[6:9], v[34:37], v[166:169]
	s_nop 0
	v_mov_b32_e32 v31, v30
	s_nop 1
	v_permlane32_swap_b32_e32 v30, v31
	v_mfma_f32_16x16x32_bf16 v[6:9], v[6:9], v[170:173], v[162:165]
	v_add_f32_e32 v57, v30, v31
	s_nop 0
	v_readlane_b32 s16, v57, 0
	v_readlane_b32 s17, v57, 1
	v_readlane_b32 s18, v57, 2
	v_readlane_b32 s19, v57, 3
	v_mov_b32_e32 v30, s16
	v_mov_b32_e32 v31, s17
	v_mov_b32_e32 v42, s18
	v_mov_b32_e32 v57, s19
	s_and_saveexec_b64 s[14:15], s[6:7]
	s_cbranch_execz .LBB0_977
	s_waitcnt lgkmcnt(0)
	v_div_scale_f32 v59, s[16:17], v57, v57, 1.0
	v_rcp_f32_e32 v155, v59
	s_ashr_i32 s13, s12, 31
	s_lshl_b64 s[10:11], s[10:11], 24
	v_fma_f32 v156, -v59, v155, 1.0
	v_fmac_f32_e32 v155, v156, v155
	v_div_scale_f32 v156, vcc, 1.0, v57, 1.0
	v_mul_f32_e32 v157, v156, v155
	v_fma_f32 v158, -v59, v157, v156
	v_fmac_f32_e32 v157, v158, v155
	v_fma_f32 v59, -v59, v157, v156
	v_div_scale_f32 v156, s[16:17], v42, v42, 1.0
	v_rcp_f32_e32 v158, v156
	v_div_fmas_f32 v59, v59, v155, v157
	v_div_fixup_f32 v57, v59, v57, 1.0
	v_fma_f32 v59, -v156, v158, 1.0
	v_fmac_f32_e32 v158, v59, v158
	v_div_scale_f32 v59, vcc, 1.0, v42, 1.0
	v_mul_f32_e32 v155, v59, v158
	v_fma_f32 v157, -v156, v155, v59
	v_fmac_f32_e32 v155, v157, v158
	v_fma_f32 v59, -v156, v155, v59
	v_div_scale_f32 v156, s[16:17], v31, v31, 1.0
	v_rcp_f32_e32 v157, v156
	v_div_fmas_f32 v59, v59, v158, v155
	v_div_fixup_f32 v42, v59, v42, 1.0
	v_fma_f32 v59, -v156, v157, 1.0
	v_fmac_f32_e32 v157, v59, v157
	v_div_scale_f32 v59, vcc, 1.0, v31, 1.0
	v_mul_f32_e32 v155, v59, v157
	v_fma_f32 v158, -v156, v155, v59
	v_fmac_f32_e32 v155, v158, v157
	v_fma_f32 v59, -v156, v155, v59
	v_div_scale_f32 v156, s[16:17], v30, v30, 1.0
	v_rcp_f32_e32 v158, v156
	v_div_fmas_f32 v59, v59, v157, v155
	v_div_fixup_f32 v155, v59, v31, 1.0
	s_add_u32 s16, s62, s10
	v_fma_f32 v31, -v156, v158, 1.0
	v_fmac_f32_e32 v158, v31, v158
	v_div_scale_f32 v31, vcc, 1.0, v30, 1.0
	v_mul_f32_e32 v59, v31, v158
	v_fma_f32 v157, -v156, v59, v31
	v_fmac_f32_e32 v59, v157, v158
	v_fma_f32 v31, -v156, v59, v31
	v_div_fmas_f32 v31, v31, v158, v59
	s_addc_u32 s17, s63, s11
	s_lshl_b64 s[10:11], s[12:13], 11
	v_div_fixup_f32 v156, v31, v30, 1.0
	s_add_u32 s10, s16, s10
	s_addc_u32 s11, s17, s11
	v_mov_b32_e32 v59, v43
	v_lshl_add_u64 v[30:31], s[10:11], 0, v[58:59]
	s_lshl_b32 s8, s8, 9
	v_lshl_add_u64 v[30:31], v[30:31], 0, s[8:9]
	v_mul_f32_e32 v176, v10, v156
	v_mul_f32_e32 v177, v11, v155
	v_cvt_pk_bf16_f32 v176, v176, v177
	global_store_short v[30:31], v176, off
	global_store_short_d16_hi v[30:31], v176, off offset:128
	v_mul_f32_e32 v178, v12, v42
	v_mul_f32_e32 v179, v13, v57
	v_cvt_pk_bf16_f32 v178, v178, v179
	global_store_short v[30:31], v178, off offset:256
	global_store_short_d16_hi v[30:31], v178, off offset:384
	v_mul_f32_e32 v176, v38, v156
	v_mul_f32_e32 v177, v39, v155
	v_cvt_pk_bf16_f32 v176, v176, v177
	global_store_short v[30:31], v176, off offset:32
	global_store_short_d16_hi v[30:31], v176, off offset:160
	v_mul_f32_e32 v178, v40, v42
	v_mul_f32_e32 v179, v41, v57
	v_cvt_pk_bf16_f32 v178, v178, v179
	global_store_short v[30:31], v178, off offset:288
	global_store_short_d16_hi v[30:31], v178, off offset:416
	v_mul_f32_e32 v176, v34, v156
	v_mul_f32_e32 v177, v35, v155
	v_cvt_pk_bf16_f32 v176, v176, v177
	global_store_short v[30:31], v176, off offset:64
	global_store_short_d16_hi v[30:31], v176, off offset:192
	v_mul_f32_e32 v178, v36, v42
	v_mul_f32_e32 v179, v37, v57
	v_cvt_pk_bf16_f32 v178, v178, v179
	global_store_short v[30:31], v178, off offset:320
	global_store_short_d16_hi v[30:31], v178, off offset:448
	v_mul_f32_e32 v176, v6, v156
	v_mul_f32_e32 v177, v7, v155
	v_cvt_pk_bf16_f32 v176, v176, v177
	global_store_short v[30:31], v176, off offset:96
	global_store_short_d16_hi v[30:31], v176, off offset:224
	v_mul_f32_e32 v178, v8, v42
	v_mul_f32_e32 v179, v9, v57
	v_cvt_pk_bf16_f32 v178, v178, v179
	global_store_short v[30:31], v178, off offset:352
	global_store_short_d16_hi v[30:31], v178, off offset:480
	s_branch .LBB0_977

.LBB0_1032:
	s_or_b64 exec, exec, s[4:5]
	s_add_u32 s12, s28, 0x1c000000
	s_addc_u32 s13, s29, 0
	s_waitcnt lgkmcnt(0)
	v_lshlrev_b32_e32 v1, 1, v212
	s_cmpk_lt_i32 s2, 0x200
	v_readfirstlane_b32 s16, v202
	s_cselect_b64 s[6:7], -1, 0
	s_cmpk_gt_i32 s2, 0x1ff
	v_bitop3_b32 v178, v1, v161, v159 bitop3:0x36
	s_barrier
	s_nop 0
	s_nop 0
	s_nop 0
	s_cbranch_scc1 .LBB0_1056
	s_ashr_i32 s37, s2, 31
	s_lshr_b32 s4, s37, 29
	s_add_i32 s8, s2, s4
	s_and_b32 s4, s8, -8
	s_sub_i32 s10, s2, s4
	s_cmp_gt_i32 s10, -1
	s_cbranch_scc0 .LBB0_1035
	s_lshl_b32 s9, s10, 6
	s_cbranch_execz .LBB0_1036
	s_branch .LBB0_1037
